# v18 plus phase-0 cache K/V f32-to-bf16 conversion loop de-serialised: 4 loads in flight with counted waits instead of one full round trip per load
# baseline (speedup 1.0000x reference)
; DI u32x2 pack4(f32x4 a) { u32x2 w; w.x = cvt_pk_bf16(a.x, a.y); w.y = cvt_pk_bf16(a.z, a.w); return w; }
; DI void phase_prep(const Params& p, lptr L, int tid, int lane, int wave) {
;     ...
;     { bf16_t* CB = (bf16_t*)(ws + WS_CKVB);
;       for (int m = gw; m < 2 * NB * NMEM; m += NGW) { const int r = m >> 1, isv = m & 1; const f32x4* src = (const f32x4*)((isv ? p.cmv : p.cmk) + (size_t)r * DM) + lane; u32x2* o8 = (u32x2*)(CB + (size_t)r * 2048 + isv * 1024) + lane;
; #pragma unroll
;           for (int j = 0; j < 4; ++j) o8[64 * j] = pack4(src[64 * j]); } }
.LBB0_120:
	s_ashr_i32 s2, s0, 1
	s_ashr_i32 s3, s2, 31
	s_lshl_b64 s[2:3], s[2:3], 12
	v_lshl_add_u64 v[8:9], v[2:3], 0, s[2:3]
	global_load_dwordx4 v[4:7], v[8:9], off
	global_load_dwordx4 v[12:15], v[8:9], off offset:1024
	global_load_dwordx4 v[16:19], v[8:9], off offset:2048
	global_load_dwordx4 v[20:23], v[8:9], off offset:3072
	v_lshl_add_u64 v[10:11], v[0:1], 0, s[2:3]
	s_add_i32 s0, s0, s24
	s_cmpk_gt_i32 s0, 0x1fff
	s_waitcnt vmcnt(3)
	v_cvt_pk_bf16_f32 v4, v4, v5
	v_cvt_pk_bf16_f32 v5, v6, v7
	global_store_dwordx2 v[10:11], v[4:5], off
	s_waitcnt vmcnt(3)
	v_cvt_pk_bf16_f32 v12, v12, v13
	v_cvt_pk_bf16_f32 v13, v14, v15
	global_store_dwordx2 v[10:11], v[12:13], off offset:512
	s_waitcnt vmcnt(3)
	v_cvt_pk_bf16_f32 v16, v16, v17
	v_cvt_pk_bf16_f32 v17, v18, v19
	global_store_dwordx2 v[10:11], v[16:17], off offset:1024
	s_waitcnt vmcnt(3)
	v_cvt_pk_bf16_f32 v20, v20, v21
	v_cvt_pk_bf16_f32 v21, v22, v23
	global_store_dwordx2 v[10:11], v[20:21], off offset:1536
	s_cbranch_scc0 .LBB0_120
